# GEMM k-loop: counted vmcnt waits in front of the 12 LDS tile writes; row-rsqrt partial loads issued during the last k-step
# speedup vs baseline: 1.0875x; 1.0185x over previous
; #define GLOADS(K0) { _Pragma("unroll") for (int i = 0; i < 8; ++i) ra[i] = *(const u32x4*)(Ap + (size_t)(32 * i) * lda + (K0)); \
;                      _Pragma("unroll") for (int i = 0; i < 4; ++i) rb[i] = *(const u32x4*)(Bp + (size_t)(32 * i) * ldb + (K0)); }
; DI void gemm_phase_(const GemmDesc& d, unsigned char* smem, const XMap& xm) {
;     ...
;   for (int tile = tstart; tile < tend; tile += tstep) {
;     DECODE(tile, z, mt, nt);
;     Ap = A + z * sA + (size_t)(mt * 256 + lrow) * lda + lcc;
;     Bp = Bt + z * sB + (size_t)(nt * 128 + lrow) * ldb + lcc;
;     GLOADS(0);
;     f32x16 acc[4][2];
; #pragma unroll
;     for (int i = 0; i < 4; ++i)
; #pragma unroll
;       for (int j = 0; j < 2; ++j)
; #pragma unroll
;         for (int r = 0; r < 16; ++r) acc[i][j][r] = 0.f;
.LBB0_613:
	s_ashr_i32 s15, s14, 31
	v_readlane_b32 s18, v249, 19
	v_readlane_b32 s19, v249, 20
	s_mul_hi_u32 s3, s18, s14
	s_mul_i32 s10, s18, s15
	s_add_i32 s3, s3, s10
	s_mul_i32 s10, s19, s14
	s_add_i32 s11, s3, s10
	s_mul_i32 s10, s18, s14
	s_lshl_b64 s[10:11], s[10:11], 1
	v_readlane_b32 s18, v249, 26
	v_readlane_b32 s19, v249, 27
	s_add_u32 s10, s18, s10
	s_addc_u32 s11, s19, s11
	s_lshl_b32 s59, s67, 8
	s_waitcnt lgkmcnt(0)
	v_add_u32_e32 v0, s59, v213
	v_mad_i64_i32 v[0:1], s[18:19], v0, s48, 0
	v_lshl_add_u64 v[0:1], v[0:1], 1, s[10:11]
	s_mul_hi_u32 s3, s4, s14
	s_mul_i32 s10, s4, s15
	s_add_i32 s3, s3, s10
	s_mul_i32 s10, s5, s14
	s_add_i32 s11, s3, s10
	s_mul_i32 s10, s4, s14
	s_lshl_b64 s[10:11], s[10:11], 1
	s_add_u32 s10, s50, s10
	v_mov_b32_e32 v197, v177
	s_addc_u32 s11, s51, s11
	s_lshl_b32 s58, s2, 7
	v_readlane_b32 s2, v252, 60
	v_lshl_add_u64 v[198:199], v[0:1], 0, v[196:197]
	v_add_u32_e32 v0, s58, v213
	v_readlane_b32 s3, v252, 61
	v_mad_i64_i32 v[0:1], s[2:3], v0, s2, 0
	v_lshl_add_u64 v[0:1], v[0:1], 1, s[10:11]
	v_readlane_b32 s2, v249, 44
	v_lshl_add_u64 v[200:201], v[0:1], 0, v[196:197]
	v_readlane_b32 s3, v249, 45
	s_mov_b32 s28, 64
	s_nop 0
	v_lshl_add_u64 v[0:1], s[2:3], 1, v[200:201]
	v_readlane_b32 s2, v248, 14
	v_readlane_b32 s3, v248, 15
	s_nop 1
	v_lshl_add_u64 v[2:3], v[0:1], 0, s[2:3]
	v_lshl_add_u64 v[4:5], v[2:3], 0, s[2:3]
	v_readlane_b32 s2, v249, 42
	v_readlane_b32 s3, v249, 43
	global_load_dwordx4 v[152:155], v[2:3], off
	global_load_dwordx4 v[128:131], v[4:5], off
	global_load_dwordx4 v[172:175], v[0:1], off
	global_load_dwordx4 v[132:135], v[200:201], off
	v_lshl_add_u64 v[0:1], s[2:3], 1, v[198:199]
	v_lshl_add_u64 v[2:3], v[0:1], 0, s[6:7]
	global_load_dwordx4 v[148:151], v[0:1], off
	global_load_dwordx4 v[136:139], v[2:3], off
	v_lshl_add_u64 v[0:1], v[2:3], 0, s[6:7]
	v_lshl_add_u64 v[2:3], v[0:1], 0, s[6:7]
	global_load_dwordx4 v[156:159], v[0:1], off
	global_load_dwordx4 v[160:163], v[2:3], off
	v_lshl_add_u64 v[0:1], v[2:3], 0, s[6:7]
	v_lshl_add_u64 v[2:3], v[0:1], 0, s[6:7]
	global_load_dwordx4 v[164:167], v[0:1], off
	global_load_dwordx4 v[168:171], v[2:3], off
	v_lshl_add_u64 v[0:1], v[2:3], 0, s[6:7]
	global_load_dwordx4 v[140:143], v[0:1], off
	global_load_dwordx4 v[144:147], v[198:199], off
	v_mov_b32_e32 v0, 0
	s_mov_b32 s2, 0
	v_mov_b32_e32 v1, v0
	v_mov_b32_e32 v2, v0
	v_mov_b32_e32 v3, v0
	v_mov_b32_e32 v4, v0
	v_mov_b32_e32 v5, v0
	v_mov_b32_e32 v6, v0
	v_mov_b32_e32 v7, v0
	v_mov_b32_e32 v8, v0
	v_mov_b32_e32 v9, v0
	v_mov_b32_e32 v10, v0
	v_mov_b32_e32 v11, v0
	v_mov_b32_e32 v12, v0
	v_mov_b32_e32 v13, v0
	v_mov_b32_e32 v14, v0
	v_mov_b32_e32 v15, v0
	v_mov_b32_e32 v32, v0
	v_mov_b32_e32 v33, v0
	v_mov_b32_e32 v34, v0
	v_mov_b32_e32 v35, v0
	v_mov_b32_e32 v36, v0
	v_mov_b32_e32 v37, v0
	v_mov_b32_e32 v38, v0
	v_mov_b32_e32 v39, v0
	v_mov_b32_e32 v40, v0
	v_mov_b32_e32 v41, v0
	v_mov_b32_e32 v42, v0
	v_mov_b32_e32 v43, v0
	v_mov_b32_e32 v44, v0
	v_mov_b32_e32 v45, v0
	v_mov_b32_e32 v46, v0
	v_mov_b32_e32 v47, v0
	v_mov_b32_e32 v16, v0
	v_mov_b32_e32 v17, v0
	v_mov_b32_e32 v18, v0
	v_mov_b32_e32 v19, v0
	v_mov_b32_e32 v20, v0
	v_mov_b32_e32 v21, v0
	v_mov_b32_e32 v22, v0
	v_mov_b32_e32 v23, v0
	v_mov_b32_e32 v24, v0
	v_mov_b32_e32 v25, v0
	v_mov_b32_e32 v26, v0
	v_mov_b32_e32 v27, v0
	v_mov_b32_e32 v28, v0
	v_mov_b32_e32 v29, v0
	v_mov_b32_e32 v30, v0
	v_mov_b32_e32 v31, v0
	v_mov_b32_e32 v48, v0
	v_mov_b32_e32 v49, v0
	v_mov_b32_e32 v50, v0
	v_mov_b32_e32 v51, v0
	v_mov_b32_e32 v52, v0
	v_mov_b32_e32 v53, v0
	v_mov_b32_e32 v54, v0
	v_mov_b32_e32 v55, v0
	v_mov_b32_e32 v56, v0
	v_mov_b32_e32 v57, v0
	v_mov_b32_e32 v58, v0
	v_mov_b32_e32 v59, v0
	v_mov_b32_e32 v60, v0
	v_mov_b32_e32 v61, v0
	v_mov_b32_e32 v62, v0
	v_mov_b32_e32 v63, v0
	v_mov_b32_e32 v64, v0
	v_mov_b32_e32 v65, v0
	v_mov_b32_e32 v66, v0
	v_mov_b32_e32 v67, v0
	v_mov_b32_e32 v68, v0
	v_mov_b32_e32 v69, v0
	v_mov_b32_e32 v70, v0
	v_mov_b32_e32 v71, v0
	v_mov_b32_e32 v72, v0
	v_mov_b32_e32 v73, v0
	v_mov_b32_e32 v74, v0
	v_mov_b32_e32 v75, v0
	v_mov_b32_e32 v76, v0
	v_mov_b32_e32 v77, v0
	v_mov_b32_e32 v78, v0
	v_mov_b32_e32 v79, v0
	v_mov_b32_e32 v96, v0
	v_mov_b32_e32 v97, v0
	v_mov_b32_e32 v98, v0
	v_mov_b32_e32 v99, v0
	v_mov_b32_e32 v100, v0
	v_mov_b32_e32 v101, v0
	v_mov_b32_e32 v102, v0
	v_mov_b32_e32 v103, v0
	v_mov_b32_e32 v104, v0
	v_mov_b32_e32 v105, v0
	v_mov_b32_e32 v106, v0
	v_mov_b32_e32 v107, v0
	v_mov_b32_e32 v108, v0
	v_mov_b32_e32 v109, v0
	v_mov_b32_e32 v110, v0
	v_mov_b32_e32 v111, v0
	v_mov_b32_e32 v80, v0
	v_mov_b32_e32 v81, v0
	v_mov_b32_e32 v82, v0
	v_mov_b32_e32 v83, v0
	v_mov_b32_e32 v84, v0
	v_mov_b32_e32 v85, v0
	v_mov_b32_e32 v86, v0
	v_mov_b32_e32 v87, v0
	v_mov_b32_e32 v88, v0
	v_mov_b32_e32 v89, v0
	v_mov_b32_e32 v90, v0
	v_mov_b32_e32 v91, v0
	v_mov_b32_e32 v92, v0
	v_mov_b32_e32 v93, v0
	v_mov_b32_e32 v94, v0
	v_mov_b32_e32 v95, v0
	v_mov_b32_e32 v112, v0
	v_mov_b32_e32 v113, v0
	v_mov_b32_e32 v114, v0
	v_mov_b32_e32 v115, v0
	v_mov_b32_e32 v116, v0
	v_mov_b32_e32 v117, v0
	v_mov_b32_e32 v118, v0
	v_mov_b32_e32 v119, v0
	v_mov_b32_e32 v120, v0
	v_mov_b32_e32 v121, v0
	v_mov_b32_e32 v122, v0
	v_mov_b32_e32 v123, v0
	v_mov_b32_e32 v124, v0
	v_mov_b32_e32 v125, v0
	v_mov_b32_e32 v126, v0
	v_mov_b32_e32 v127, v0
	v_lshlrev_b32_e32 v234, 2, v215
	v_add_u32_e32 v234, 0xde20, v234
	ds_write_b128 v234, v[202:205]
	ds_write_b128 v234, v[208:211] offset:4096
	ds_write_b128 v234, v[180:183] offset:8192
	ds_write_b128 v234, v[184:187] offset:12288
	ds_write_b128 v234, v[192:195] offset:16384
	s_waitcnt vmcnt(0)
; #define MFMA32(a, b, c) __builtin_amdgcn_mfma_f32_32x32x16_bf16((a), (b), (c), 0, 0, 0)
; #define GLOADS(K0) { _Pragma("unroll") for (int i = 0; i < 8; ++i) ra[i] = *(const u32x4*)(Ap + (size_t)(32 * i) * lda + (K0)); \
;                      _Pragma("unroll") for (int i = 0; i < 4; ++i) rb[i] = *(const u32x4*)(Bp + (size_t)(32 * i) * ldb + (K0)); }
; DI void gemm_phase_(const GemmDesc& d, unsigned char* smem, const XMap& xm) {
;     ...
;     for (int kt = 0; kt < KT; ++kt) {
;       __syncthreads();
; #pragma unroll
;       for (int i = 0; i < 8; ++i) *(u32x4*)(sAq + (lrow + 32 * i) * GLD + lcc) = ra[i];
; #pragma unroll
;       for (int i = 0; i < 4; ++i) *(u32x4*)(sBq + (lrow + 32 * i) * GLD + lcc) = rb[i];
;       __syncthreads();
;       if (kt + 1 < KT) GLOADS((kt + 1) * 64);
;       __builtin_amdgcn_s_setprio(3);
; #pragma unroll
;       for (int ks = 0; ks < 4; ++ks) {
;         bf16x8 bq[2];
; #pragma unroll
;         for (int j = 0; j < 2; ++j) bq[j] = *(const bf16x8*)(sBq + (wn * 64 + j * 32 + l32) * GLD + ks * 16 + half * 8);
; #pragma unroll
;         for (int ih = 0; ih < 2; ++ih) {
;           bf16x8 af[2];
; #pragma unroll
;           for (int i = 0; i < 2; ++i) af[i] = *(const bf16x8*)(sAq + (wm * 128 + (ih * 2 + i) * 32 + l32) * GLD + ks * 16 + half * 8);
; #pragma unroll
;           for (int i = 0; i < 2; ++i)
; #pragma unroll
;             for (int j = 0; j < 2; ++j) acc[ih * 2 + i][j] = MFMA32(af[i], bq[j], acc[ih * 2 + i][j]);
;         }
;       }
;       __builtin_amdgcn_s_setprio(0);
;     }
;     ...
;     if (rpart) {
;       {
;         const float* pp = rpart + (size_t)(mtc * 256 + tid) * 16;
;         float sm = 0.f;
; #pragma unroll
;         for (int q = 0; q < 4; ++q) { const f32x4 v = *(const f32x4*)(pp + q * 4); sm += v[0]; sm += v[1]; sm += v[2]; sm += v[3]; }
;         rsl[tid] = rsqrtf(sm * (1.f / DM) + EPS);
.LBB0_615:
	s_add_i32 s2, s2, 1
	s_cmp_ge_i32 s2, s66
	s_barrier
	s_waitcnt vmcnt(11)
	ds_write_b128 v229, v[144:147]
	s_waitcnt vmcnt(10)
	ds_write_b128 v229, v[140:143] offset:4608
	s_waitcnt vmcnt(9)
	ds_write_b128 v229, v[168:171] offset:9216
	s_waitcnt vmcnt(8)
	ds_write_b128 v229, v[164:167] offset:13824
	s_waitcnt vmcnt(7)
	ds_write_b128 v229, v[160:163] offset:18432
	s_waitcnt vmcnt(6)
	ds_write_b128 v229, v[156:159] offset:23040
	s_waitcnt vmcnt(5)
	ds_write_b128 v229, v[136:139] offset:27648
	s_waitcnt vmcnt(4)
	ds_write_b128 v229, v[148:151] offset:32256
	s_waitcnt vmcnt(3)
	ds_write_b128 v229, v[132:135] offset:36864
	s_waitcnt vmcnt(2)
	ds_write_b128 v229, v[128:131] offset:41472
	s_waitcnt vmcnt(1)
	ds_write_b128 v229, v[152:155] offset:46080
	s_waitcnt vmcnt(0)
	ds_write_b128 v229, v[172:175] offset:50688
	s_waitcnt lgkmcnt(0)
	s_barrier
	ds_read_b128 v[234:237], v231
	ds_read_b128 v[238:241], v230 offset:36864
	ds_read_b128 v[242:245], v230 offset:41472
	ds_read_b128 v[202:205], v231 offset:4608
	ds_read_b128 v[208:211], v231 offset:9216
	ds_read_b128 v[180:183], v232
	ds_read_b128 v[184:187], v230 offset:36896
	ds_read_b128 v[192:195], v230 offset:41504
	s_cbranch_scc1 .Lgemm_mfma_last
	s_lshl_b64 s[10:11], s[28:29], 1
	v_lshl_add_u64 v[128:129], v[198:199], 0, s[10:11]
	v_lshl_add_u64 v[130:131], s[8:9], 1, v[128:129]
	global_load_dwordx4 v[144:147], v[128:129], off
	global_load_dwordx4 v[140:143], v[130:131], off
	s_setprio 3
	s_waitcnt lgkmcnt(5)
	v_mfma_f32_32x32x16_bf16 v[112:127], v[234:237], v[238:241], v[112:127]
	v_mfma_f32_32x32x16_bf16 v[80:95], v[234:237], v[242:245], v[80:95]
	ds_read_b128 v[234:237], v231 offset:32
	v_lshl_add_u64 v[128:129], v[130:131], 0, s[34:35]
	v_lshl_add_u64 v[130:131], v[128:129], 0, s[34:35]
	global_load_dwordx4 v[168:171], v[128:129], off
	global_load_dwordx4 v[164:167], v[130:131], off
	s_waitcnt lgkmcnt(5)
	v_mfma_f32_32x32x16_bf16 v[96:111], v[202:205], v[238:241], v[96:111]
	v_mfma_f32_32x32x16_bf16 v[64:79], v[202:205], v[242:245], v[64:79]
	ds_read_b128 v[202:205], v231 offset:4640
	v_lshl_add_u64 v[128:129], v[130:131], 0, s[34:35]
	v_lshl_add_u64 v[130:131], v[128:129], 0, s[34:35]
	global_load_dwordx4 v[160:163], v[128:129], off
	global_load_dwordx4 v[156:159], v[130:131], off
	s_waitcnt lgkmcnt(5)
	v_mfma_f32_32x32x16_bf16 v[48:63], v[208:211], v[238:241], v[48:63]
	v_mfma_f32_32x32x16_bf16 v[16:31], v[208:211], v[242:245], v[16:31]
	ds_read_b128 v[208:211], v231 offset:9248
	v_lshl_add_u64 v[128:129], v[130:131], 0, s[34:35]
	global_load_dwordx4 v[136:139], v[128:129], off
	v_lshl_add_u64 v[128:129], v[128:129], 0, s[34:35]
	global_load_dwordx4 v[148:151], v[128:129], off
	s_waitcnt lgkmcnt(5)
	v_mfma_f32_32x32x16_bf16 v[32:47], v[180:183], v[238:241], v[32:47]
	v_mfma_f32_32x32x16_bf16 v[0:15], v[180:183], v[242:245], v[0:15]
	ds_read_b128 v[180:183], v232 offset:32
	v_lshl_add_u64 v[128:129], v[200:201], 0, s[10:11]
	v_lshl_add_u64 v[152:153], s[12:13], 1, v[128:129]
	global_load_dwordx4 v[132:135], v[128:129], off
	ds_read_b128 v[238:241], v230 offset:36928
	ds_read_b128 v[242:245], v230 offset:41536
	s_waitcnt lgkmcnt(5)
	v_mfma_f32_32x32x16_bf16 v[112:127], v[234:237], v[184:187], v[112:127]
	v_mfma_f32_32x32x16_bf16 v[80:95], v[234:237], v[192:195], v[80:95]
	ds_read_b128 v[234:237], v231 offset:64
	s_nop 0
	global_load_dwordx4 v[128:131], v[152:153], off
	v_lshl_add_u64 v[152:153], v[152:153], 0, s[74:75]
	v_lshl_add_u64 v[172:173], v[152:153], 0, s[74:75]
	s_waitcnt lgkmcnt(5)
	v_mfma_f32_32x32x16_bf16 v[96:111], v[202:205], v[184:187], v[96:111]
	v_mfma_f32_32x32x16_bf16 v[64:79], v[202:205], v[192:195], v[64:79]
	ds_read_b128 v[202:205], v231 offset:4672
	global_load_dwordx4 v[152:155], v[152:153], off
	s_nop 0
	global_load_dwordx4 v[172:175], v[172:173], off
	s_waitcnt lgkmcnt(5)
	v_mfma_f32_32x32x16_bf16 v[48:63], v[208:211], v[184:187], v[48:63]
	v_mfma_f32_32x32x16_bf16 v[16:31], v[208:211], v[192:195], v[16:31]
	ds_read_b128 v[208:211], v231 offset:9280
	s_waitcnt lgkmcnt(5)
	v_mfma_f32_32x32x16_bf16 v[32:47], v[180:183], v[184:187], v[32:47]
	v_mfma_f32_32x32x16_bf16 v[0:15], v[180:183], v[192:195], v[0:15]
	ds_read_b128 v[180:183], v232 offset:64
	ds_read_b128 v[184:187], v230 offset:36960
	ds_read_b128 v[192:195], v230 offset:41568
	s_waitcnt lgkmcnt(5)
	v_mfma_f32_32x32x16_bf16 v[112:127], v[234:237], v[238:241], v[112:127]
	v_mfma_f32_32x32x16_bf16 v[80:95], v[234:237], v[242:245], v[80:95]
	ds_read_b128 v[234:237], v231 offset:96
	s_waitcnt lgkmcnt(5)
	v_mfma_f32_32x32x16_bf16 v[96:111], v[202:205], v[238:241], v[96:111]
	v_mfma_f32_32x32x16_bf16 v[64:79], v[202:205], v[242:245], v[64:79]
	ds_read_b128 v[202:205], v231 offset:4704
	s_waitcnt lgkmcnt(5)
	v_mfma_f32_32x32x16_bf16 v[48:63], v[208:211], v[238:241], v[48:63]
	v_mfma_f32_32x32x16_bf16 v[16:31], v[208:211], v[242:245], v[16:31]
	ds_read_b128 v[208:211], v231 offset:9312
	s_waitcnt lgkmcnt(5)
	v_mfma_f32_32x32x16_bf16 v[32:47], v[180:183], v[238:241], v[32:47]
	v_mfma_f32_32x32x16_bf16 v[0:15], v[180:183], v[242:245], v[0:15]
	ds_read_b128 v[180:183], v232 offset:96
	s_waitcnt lgkmcnt(3)
	v_mfma_f32_32x32x16_bf16 v[112:127], v[234:237], v[184:187], v[112:127]
	v_mfma_f32_32x32x16_bf16 v[80:95], v[234:237], v[192:195], v[80:95]
	s_waitcnt lgkmcnt(2)
	v_mfma_f32_32x32x16_bf16 v[96:111], v[202:205], v[184:187], v[96:111]
	v_mfma_f32_32x32x16_bf16 v[64:79], v[202:205], v[192:195], v[64:79]
	s_waitcnt lgkmcnt(1)
	v_mfma_f32_32x32x16_bf16 v[48:63], v[208:211], v[184:187], v[48:63]
	v_mfma_f32_32x32x16_bf16 v[16:31], v[208:211], v[192:195], v[16:31]
	s_waitcnt lgkmcnt(0)
	v_mfma_f32_32x32x16_bf16 v[32:47], v[180:183], v[184:187], v[32:47]
	v_mfma_f32_32x32x16_bf16 v[0:15], v[180:183], v[192:195], v[0:15]
	s_setprio 0
	s_add_i32 s28, s28, 64
	s_branch .LBB0_615
.Lgemm_mfma_last:
	s_and_b64 vcc, exec, s[0:1]
	s_cbranch_vccz .Lgemm_norp
	v_add_u32_e32 v128, s59, v179
	v_ashrrev_i32_e32 v129, 31, v128
	v_readlane_b32 s2, v249, 22
	v_lshlrev_b64 v[128:129], 6, v[128:129]
	v_readlane_b32 s3, v249, 23
	s_nop 1
	v_lshl_add_u64 v[140:141], s[2:3], 0, v[128:129]
	global_load_dwordx4 v[128:131], v[140:141], off
	global_load_dwordx4 v[132:135], v[140:141], off offset:16
	global_load_dwordx4 v[136:139], v[140:141], off offset:32
	s_nop 0
	global_load_dwordx4 v[140:143], v[140:141], off offset:48

; DI void gemm_phase_(const GemmDesc& d, unsigned char* smem, const XMap& xm) {
;     ...
;     const int zc = z, mtc = mt, ntc = nt;
;     __syncthreads();
;     float* rsl = (float*)smem + 13824;
;     if (rpart) {
;       {
;         const float* pp = rpart + (size_t)(mtc * 256 + tid) * 16;
;         float sm = 0.f;
; #pragma unroll
;         for (int q = 0; q < 4; ++q) { const f32x4 v = *(const f32x4*)(pp + q * 4); sm += v[0]; sm += v[1]; sm += v[2]; sm += v[3]; }
;         rsl[tid] = rsqrtf(sm * (1.f / DM) + EPS);
;       }
;       __syncthreads();
.LBB0_617:
	v_lshlrev_b32_e32 v234, 2, v215
	v_add_u32_e32 v234, 0xde20, v234
	ds_read_b128 v[202:205], v234
	ds_read_b128 v[208:211], v234 offset:4096
	ds_read_b128 v[180:183], v234 offset:8192
	ds_read_b128 v[184:187], v234 offset:12288
	ds_read_b128 v[192:195], v234 offset:16384
	s_waitcnt lgkmcnt(0)
	s_and_b64 vcc, exec, s[0:1]
	s_barrier
	s_cbranch_vccz .LBB0_619
	s_waitcnt vmcnt(3)
	v_add_f32_e32 v128, 0, v128
	v_add_f32_e32 v128, v129, v128
	v_add_f32_e32 v128, v130, v128
	v_add_f32_e32 v128, v131, v128
	s_waitcnt vmcnt(2)
	v_add_f32_e32 v128, v132, v128
	v_add_f32_e32 v128, v133, v128
	v_add_f32_e32 v128, v134, v128
	v_add_f32_e32 v128, v135, v128
	s_waitcnt vmcnt(1)
	v_add_f32_e32 v128, v136, v128
	v_add_f32_e32 v128, v137, v128
	v_add_f32_e32 v128, v138, v128
	v_add_f32_e32 v128, v139, v128
	s_waitcnt vmcnt(0)
	v_add_f32_e32 v128, v140, v128
	v_add_f32_e32 v128, v141, v128
	v_add_f32_e32 v128, v142, v128
	v_add_f32_e32 v128, v143, v128
	v_fmamk_f32 v128, v128, 0x3a800000, v193
	v_mul_f32_e32 v129, 0x4b800000, v128
	v_cmp_gt_f32_e32 vcc, s97, v128
	s_nop 1
	v_cndmask_b32_e32 v128, v128, v129, vcc
	v_rsq_f32_e32 v128, v128
	s_nop 0
	v_mul_f32_e32 v129, 0x45800000, v128
	v_cndmask_b32_e32 v128, v128, v129, vcc
	ds_write_b32 v215, v128 offset:55296
	s_waitcnt lgkmcnt(0)
	s_barrier
